# P0 weight-conversion queue: moved the s_waitcnt for the returning atomic draw from right behind the atomic to its first consumer (next iteration header); dropped the identity readfirstlane fix-up; bit
# speedup vs baseline: 1.0042x; 1.0040x over previous
; __device__ __forceinline__ void p0_prologue(LAS unsigned char* lds_, const Params& p) {
;     ...
;         for (;;) {
;             const int it = (int)__builtin_amdgcn_readfirstlane(qraw) * NWAVES + F.wave; if (it >= NITEMS - N_DEFER) break;
;             if (F.lane == 0) qraw = __hip_atomic_fetch_add(qh, 1u, __ATOMIC_RELAXED, __HIP_MEMORY_SCOPE_AGENT);
;             int r = it;
;             if (r < I_IN) { const int kb = r / NB_IN, nb = r % NB_IN;
.LBB0_31:
	s_waitcnt vmcnt(0)
	v_readfirstlane_b32 s4, v13
	s_lshl_b32 s18, s4, 3
	s_add_i32 s18, s18, s14
	s_cmp_gt_i32 s18, 0xa83f
	s_mov_b64 s[4:5], -1
	s_cbranch_scc1 .LBB0_30
	s_and_saveexec_b64 s[4:5], s[0:1]
	s_cbranch_execnz .LBB0_35
	s_or_b64 exec, exec, s[4:5]
	s_cmpk_gt_i32 s18, 0x283f
	s_mov_b64 s[4:5], -1
	s_cbranch_scc1 .LBB0_38

; __device__ __forceinline__ void p0_prologue(LAS unsigned char* lds_, const Params& p) {
;     ...
;             if (F.lane == 0) qraw = __hip_atomic_fetch_add(qh, 1u, __ATOMIC_RELAXED, __HIP_MEMORY_SCOPE_AGENT);
;             int r = it;
;             if (r < I_IN) { const int kb = r / NB_IN, nb = r % NB_IN;
.LBB0_37:
	s_or_b64 exec, exec, s[10:11]
	s_or_b64 exec, exec, s[4:5]
	s_cmpk_gt_i32 s18, 0x283f
	s_mov_b64 s[4:5], -1
	s_cbranch_scc0 .LBB0_34
